# v29: v25 + one static s_setprio 1 for waves 4-7 during the RG-LRU final pass and forgetting-attention phase (no per-segment toggling)
# baseline (speedup 1.0000x reference)
; __global__ void __launch_bounds__(NTHR, 2) hybrid_fwd(Args args) {
;     ...
;         GSYNC();
;         for (int it = vcu; it < 512; it += G)
.LBB0_835:
	s_or_b64 exec, exec, s[0:1]
	v_readfirstlane_b32 s0, v197
	s_nop 3
	s_lshr_b32 s0, s0, 6
	s_cmp_ge_u32 s0, 4
	s_cbranch_scc0 .Lp5_prio_done
	s_setprio 1
.Lp5_prio_done:
	v_readlane_b32 s0, v254, 0
	v_mov_b32_e32 v126, v197
	s_mov_b32 s20, s0
	v_readlane_b32 s21, v254, 2
	s_waitcnt lgkmcnt(0)
	s_barrier
	s_and_b32 s0, s20, 7
	s_cmp_eq_u32 s0, 0
	v_readlane_b32 s1, v254, 1
	s_cbranch_scc0 .LBB0_837
	s_ashr_i32 s1, s21, 31
	s_lshr_b32 s1, s1, 29
	s_add_i32 s1, s21, s1
	s_ashr_i32 s2, s1, 3
	s_and_b32 s1, s1, -8
	s_ashr_i32 s0, s20, 3
	s_sub_i32 s1, s21, s1
	s_mul_i32 s0, s1, s0
	s_add_i32 s21, s0, s2

; __device__ __forceinline__ unsigned xb_ld(unsigned* p)              { return __hip_atomic_load(p, __ATOMIC_RELAXED, __HIP_MEMORY_SCOPE_AGENT); }
; __device__ __forceinline__ void xcd_barrier_complete(unsigned* bar, unsigned x, unsigned& nloc, unsigned& nx) {
;     const unsigned G = gridDim.x * gridDim.y * gridDim.z;
;     unsigned sum, cnt, mine, sp = 0u;
;     for (;;) {
;         sum = 0u; cnt = 0u; mine = 0u;
; #pragma unroll
;         for (unsigned j = 0; j < 16; ++j) { const unsigned c = xb_ld(&bar[XB_XCNT(j)]); sum += c; cnt += (c > 0u) ? 1u : 0u; mine = (j == x) ? c : mine; }
;         if (sum == G) break;
;         __builtin_amdgcn_s_sleep(1);
;         if ((++sp & 255u) == 0u) { if (xb_ld(&bar[XB_TMO])) break; if (sp > XB_SPIN_CAP) { atomicAdd(&bar[XB_TMO], 1u); break; } }
;     }
;     nloc = mine > 0u ? mine : 1u; nx = cnt > 0u ? cnt : 1u;
; }
; __device__ __forceinline__ void xcd_barrier(const XcdBarrier& b) {
;     asm volatile("s_waitcnt vmcnt(0)" ::: "memory");
;     __syncthreads();
;     if (threadIdx.x == 0) {
;         unsigned* bar = b.bar;
;         __builtin_amdgcn_s_waitcnt(0);
;         unsigned nloc = b.st[0], nx = b.st[1];
;         if (nloc == 0u) { xcd_barrier_complete(bar, b.x, nloc, nx); b.st[0] = nloc; b.st[1] = nx; }
.LBB0_962:
	s_waitcnt vmcnt(0) lgkmcnt(0)
	s_setprio 0
	s_getreg_b32 s2, hwreg(HW_REG_XCC_ID, 0, 4)
	s_waitcnt vmcnt(0)
	s_barrier
	s_mov_b64 s[0:1], exec
	v_readlane_b32 s4, v254, 5
	v_readlane_b32 s5, v254, 6
	s_and_b64 s[4:5], s[0:1], s[4:5]
	s_mov_b64 exec, s[4:5]
	s_cbranch_execz .LBB0_1014
	v_readlane_b32 s3, v254, 36
	s_waitcnt vmcnt(0) expcnt(0) lgkmcnt(0)
	s_and_b32 s22, s2, 15
	v_mov_b32_e32 v0, s3
	ds_read_b32 v2, v0
	v_readlane_b32 s3, v254, 37
	s_waitcnt lgkmcnt(0)
	v_cmp_ne_u32_e32 vcc, 0, v2
	v_mov_b32_e32 v0, s3
	ds_read_b32 v0, v0
	s_cbranch_vccnz .LBB0_978
	s_add_u32 s2, s82, 0xc0200
	s_addc_u32 s3, s83, 0
	s_add_u32 s4, s82, 0xc0400
	s_addc_u32 s5, s83, 0
	s_add_u32 s6, s82, 0xc0500
	s_addc_u32 s7, s83, 0
	s_add_u32 s8, s82, 0xc0600
	s_addc_u32 s9, s83, 0
	s_add_u32 s10, s82, 0xc0700
	s_addc_u32 s11, s83, 0
	s_add_u32 s12, s82, 0xc0800
	s_addc_u32 s13, s83, 0
	s_add_u32 s14, s82, 0xc0900
	s_addc_u32 s15, s83, 0
	s_add_u32 s16, s82, 0xc0a00
	s_addc_u32 s17, s83, 0
	s_add_u32 s18, s82, 0xc0b00
	s_addc_u32 s19, s83, 0
	s_add_u32 s20, s82, 0xc0c00
	s_addc_u32 s21, s83, 0
	s_add_u32 s30, s82, 0xc0d00
	s_addc_u32 s31, s83, 0
	s_add_u32 s44, s82, 0xc0e00
	s_addc_u32 s45, s83, 0
	s_add_u32 s62, s82, 0xc0f00
	s_addc_u32 s63, s83, 0
	s_add_u32 s64, s82, 0xc1000
	s_addc_u32 s65, s83, 0
	s_add_u32 s68, s82, 0xc1100
	s_addc_u32 s69, s83, 0
	s_add_u32 s70, s82, 0xc1200
	s_addc_u32 s71, s83, 0
	s_add_u32 s80, s82, 0xc1300
	s_mov_b32 s34, s94
	s_addc_u32 s81, s83, 0
	s_mov_b32 s23, 1
	s_branch .LBB0_966
